# non-temporal (nt) hint on the 16 streaming fp32 weight loads of the phase-4 weight conversion
# speedup vs baseline: 1.0157x; 1.0032x over previous
.LBB0_291:
	s_lshl_b32 s27, s27, 6
	v_or_b32_e32 v2, s27, v4
	s_add_i32 s55, s22, -1
	s_lshl_b32 s54, s25, 6
	v_min_i32_e32 v2, s55, v2
	v_ashrrev_i32_e32 v3, 31, v2
	v_add_u32_e32 v53, s54, v5
	v_lshl_add_u64 v[2:3], v[2:3], 2, s[52:53]
	v_mad_u64_u32 v[54:55], s[52:53], v53, s22, 0
	v_ashrrev_i32_e32 v57, 31, v53
	v_mov_b32_e32 v56, v55
	v_mad_u64_u32 v[56:57], s[52:53], v57, s22, v[56:57]
	v_mov_b32_e32 v55, v56
	v_lshl_add_u64 v[54:55], v[54:55], 2, v[2:3]
	s_waitcnt vmcnt(63) expcnt(7) lgkmcnt(15)
	s_barrier
	global_load_dword v53, v[54:55], off nt
	v_add_u32_e32 v54, s54, v6
	v_ashrrev_i32_e32 v57, 31, v54
	v_mad_u64_u32 v[54:55], s[52:53], v54, s22, 0
	v_mov_b32_e32 v56, v55
	v_mad_u64_u32 v[56:57], s[52:53], v57, s22, v[56:57]
	v_mov_b32_e32 v55, v56
	v_lshl_add_u64 v[54:55], v[54:55], 2, v[2:3]
	global_load_dword v58, v[54:55], off nt
	v_add_u32_e32 v54, s54, v7
	v_ashrrev_i32_e32 v57, 31, v54
	v_mad_u64_u32 v[54:55], s[52:53], v54, s22, 0
	v_mov_b32_e32 v56, v55
	v_mad_u64_u32 v[56:57], s[52:53], v57, s22, v[56:57]
	v_mov_b32_e32 v55, v56
	v_lshl_add_u64 v[54:55], v[54:55], 2, v[2:3]
	global_load_dword v59, v[54:55], off nt
	v_add_u32_e32 v54, s54, v8
	v_ashrrev_i32_e32 v57, 31, v54
	v_mad_u64_u32 v[54:55], s[52:53], v54, s22, 0
	v_mov_b32_e32 v56, v55
	v_mad_u64_u32 v[56:57], s[52:53], v57, s22, v[56:57]
	v_mov_b32_e32 v55, v56
	v_lshl_add_u64 v[54:55], v[54:55], 2, v[2:3]
	global_load_dword v60, v[54:55], off nt
	v_add_u32_e32 v54, s54, v9
	v_ashrrev_i32_e32 v57, 31, v54
	v_mad_u64_u32 v[54:55], s[52:53], v54, s22, 0
	v_mov_b32_e32 v56, v55
	v_mad_u64_u32 v[56:57], s[52:53], v57, s22, v[56:57]
	v_mov_b32_e32 v55, v56
	v_lshl_add_u64 v[54:55], v[54:55], 2, v[2:3]
	global_load_dword v61, v[54:55], off nt
	v_add_u32_e32 v54, s54, v10
	v_ashrrev_i32_e32 v57, 31, v54
	v_mad_u64_u32 v[54:55], s[52:53], v54, s22, 0
	v_mov_b32_e32 v56, v55
	v_mad_u64_u32 v[56:57], s[52:53], v57, s22, v[56:57]
	v_mov_b32_e32 v55, v56
	v_lshl_add_u64 v[54:55], v[54:55], 2, v[2:3]
	global_load_dword v62, v[54:55], off nt
	v_add_u32_e32 v54, s54, v11
	v_ashrrev_i32_e32 v57, 31, v54
	v_mad_u64_u32 v[54:55], s[52:53], v54, s22, 0
	v_mov_b32_e32 v56, v55
	v_mad_u64_u32 v[56:57], s[52:53], v57, s22, v[56:57]
	v_mov_b32_e32 v55, v56
	v_lshl_add_u64 v[54:55], v[54:55], 2, v[2:3]
	global_load_dword v63, v[54:55], off nt
	v_add_u32_e32 v54, s54, v12
	v_ashrrev_i32_e32 v57, 31, v54
	v_mad_u64_u32 v[54:55], s[52:53], v54, s22, 0
	v_mov_b32_e32 v56, v55
	v_mad_u64_u32 v[56:57], s[52:53], v57, s22, v[56:57]
	v_mov_b32_e32 v55, v56
	v_lshl_add_u64 v[54:55], v[54:55], 2, v[2:3]
	global_load_dword v64, v[54:55], off nt
	v_add_u32_e32 v54, s54, v13
	v_ashrrev_i32_e32 v57, 31, v54
	v_mad_u64_u32 v[54:55], s[52:53], v54, s22, 0
	v_mov_b32_e32 v56, v55
	v_mad_u64_u32 v[56:57], s[52:53], v57, s22, v[56:57]
	v_mov_b32_e32 v55, v56
	v_lshl_add_u64 v[54:55], v[54:55], 2, v[2:3]
	global_load_dword v65, v[54:55], off nt
	v_add_u32_e32 v54, s54, v14
	v_ashrrev_i32_e32 v57, 31, v54
	v_mad_u64_u32 v[54:55], s[52:53], v54, s22, 0
	v_mov_b32_e32 v56, v55
	v_mad_u64_u32 v[56:57], s[52:53], v57, s22, v[56:57]
	v_mov_b32_e32 v55, v56
	v_lshl_add_u64 v[54:55], v[54:55], 2, v[2:3]
	global_load_dword v66, v[54:55], off nt
	v_add_u32_e32 v54, s54, v15
	v_ashrrev_i32_e32 v57, 31, v54
	v_mad_u64_u32 v[54:55], s[52:53], v54, s22, 0
	v_mov_b32_e32 v56, v55
	v_mad_u64_u32 v[56:57], s[52:53], v57, s22, v[56:57]
	v_mov_b32_e32 v55, v56
	v_lshl_add_u64 v[54:55], v[54:55], 2, v[2:3]
	global_load_dword v67, v[54:55], off nt
	v_add_u32_e32 v54, s54, v16
	v_ashrrev_i32_e32 v57, 31, v54
	v_mad_u64_u32 v[54:55], s[52:53], v54, s22, 0
	v_mov_b32_e32 v56, v55
	v_mad_u64_u32 v[56:57], s[52:53], v57, s22, v[56:57]
	v_mov_b32_e32 v55, v56
	v_lshl_add_u64 v[54:55], v[54:55], 2, v[2:3]
	global_load_dword v68, v[54:55], off nt
	v_add_u32_e32 v54, s54, v17
	v_ashrrev_i32_e32 v57, 31, v54
	v_mad_u64_u32 v[54:55], s[52:53], v54, s22, 0
	v_mov_b32_e32 v56, v55
	v_mad_u64_u32 v[56:57], s[52:53], v57, s22, v[56:57]
	v_mov_b32_e32 v55, v56
	v_lshl_add_u64 v[54:55], v[54:55], 2, v[2:3]
	global_load_dword v69, v[54:55], off nt
	v_add_u32_e32 v54, s54, v18
	v_ashrrev_i32_e32 v57, 31, v54
	v_mad_u64_u32 v[54:55], s[52:53], v54, s22, 0
	v_mov_b32_e32 v56, v55
	v_mad_u64_u32 v[56:57], s[52:53], v57, s22, v[56:57]
	v_mov_b32_e32 v55, v56
	v_lshl_add_u64 v[54:55], v[54:55], 2, v[2:3]
	global_load_dword v70, v[54:55], off nt
	v_add_u32_e32 v54, s54, v19
	v_ashrrev_i32_e32 v57, 31, v54
	v_mad_u64_u32 v[54:55], s[52:53], v54, s22, 0
	v_mov_b32_e32 v56, v55
	v_mad_u64_u32 v[56:57], s[52:53], v57, s22, v[56:57]
	v_mov_b32_e32 v55, v56
	v_lshl_add_u64 v[54:55], v[54:55], 2, v[2:3]
	global_load_dword v71, v[54:55], off nt
	v_add_u32_e32 v54, s54, v20
	v_ashrrev_i32_e32 v57, 31, v54
	v_mad_u64_u32 v[54:55], s[52:53], v54, s22, 0
	v_mov_b32_e32 v56, v55
	v_mad_u64_u32 v[56:57], s[52:53], v57, s22, v[56:57]
	v_mov_b32_e32 v55, v56
	v_lshl_add_u64 v[2:3], v[54:55], 2, v[2:3]
	global_load_dword v2, v[2:3], off nt
	s_lshl_b32 s25, s25, 7
	s_add_u32 s50, s50, s25
	s_waitcnt vmcnt(15)
	ds_write_b32 v37, v53
	s_waitcnt vmcnt(14)
	ds_write_b32 v38, v58
	s_waitcnt vmcnt(13)
	ds_write_b32 v39, v59
	s_waitcnt vmcnt(12)
	ds_write_b32 v40, v60
	s_waitcnt vmcnt(11)
	ds_write_b32 v41, v61
	s_waitcnt vmcnt(10)
	ds_write_b32 v42, v62
	s_waitcnt vmcnt(9)
	ds_write_b32 v43, v63
	s_waitcnt vmcnt(8)
	ds_write_b32 v44, v64
	s_waitcnt vmcnt(7)
	ds_write_b32 v45, v65
	s_waitcnt vmcnt(6)
	ds_write_b32 v46, v66
	s_waitcnt vmcnt(5)
	ds_write_b32 v47, v67
	s_waitcnt vmcnt(4)
	ds_write_b32 v48, v68
	s_waitcnt vmcnt(3)
	ds_write_b32 v49, v69
	s_waitcnt vmcnt(2)
	ds_write_b32 v50, v70
	s_waitcnt vmcnt(1)
	ds_write_b32 v51, v71
	s_waitcnt vmcnt(0)
	ds_write_b32 v52, v2
	s_addc_u32 s51, s51, 0
	v_add_u32_e32 v53, s27, v21
	v_lshl_add_u64 v[2:3], s[50:51], 0, v[130:131]
	v_cmp_gt_i32_e32 vcc, s22, v53
	s_waitcnt lgkmcnt(0)
	s_barrier
	s_and_saveexec_b64 s[50:51], vcc
	s_cbranch_execz .LBB0_293
	ds_read2_b32 v[54:55], v22 offset1:65
	v_ashrrev_i32_e32 v56, 31, v53
	v_mul_lo_u32 v57, s49, v53
	v_mul_lo_u32 v56, s48, v56
	s_waitcnt lgkmcnt(0)
	v_cvt_pk_bf16_f32 v58, v54, v55
	v_mad_u64_u32 v[54:55], s[52:53], s48, v53, 0
	v_add3_u32 v55, v55, v56, v57
	v_lshl_add_u64 v[54:55], v[54:55], 1, v[2:3]
	global_store_dword v[54:55], v58, off
